# v20 + up-GEMM epilogue: first four row-sumsq loads prefetched one tile ahead (removes an exposed memory round trip per tile)
# speedup vs baseline: 1.0202x; 1.0033x over previous
; template <class Epi, class Sched>
; __device__ __forceinline__ void gemm_phase(const int wv, LAS unsigned char* lds, const Gemm g, const Sched& S, const Epi& E) {
;     ...
;     const int tid = tid_, wid = __builtin_amdgcn_readfirstlane(tid >> 6), lane = tid & 63, wr = wid >> 2, wc = wid & 3, fr = lane & 15, fq = lane >> 4;
;     const int K = g.K, nt = K / BK;
;     unsigned voffA[2], voffB[2];
; #pragma unroll
;     for (int i = 0; i < 2; ++i) { int R, C; stage_rc(tid * 16 + i * 8192, R, C); const int Rb = Epi::PERM ? ((R & ~31) + perm32(R & 31)) : R;
;         voffA[i] = (unsigned)(R * (g.atile ? BK : g.lda) + C) * 2u; voffB[i] = (unsigned)(Rb * g.ldb + C) * 2u; }
;     const size_t kstep = (size_t)(BK * 2);
;     const int ldaE = g.atile ? BK : g.lda;
;     const size_t kstepA = g.atile ? (size_t)BM * BK * 2 : kstep;
;     const size_t hstepA = (size_t)HALF * ldaE * 2, hstepB = (size_t)HALF * g.ldb * 2;
;     const size_t tstepA = g.atile ? (size_t)(g.K / BK) * BM * BK * 2 : 2 * hstepA, tstepB = 2 * hstepB;
;     const unsigned ldsw = (unsigned)wid * 1024u;
;     const int aoff = lds_byte(wr * 64 + fr, fq * 8), boff = lds_byte(wc * 32 + fr, fq * 8);
;     ...
;     Unit cur, nxt; int ui = 0;
;     if (!S.next(0, cur)) return;
;     f32x4 acc[2][2][4][2];
; #pragma unroll
;     for (int a = 0; a < 2; ++a)
; #pragma unroll
;         for (int b = 0; b < 2; ++b)
; #pragma unroll
;             for (int m = 0; m < 4; ++m)
; #pragma unroll
;                 for (int n = 0; n < 2; ++n) acc[a][b][m][n] = (f32x4){0.f, 0.f, 0.f, 0.f};
;     bf16x8 At[4][2], B0[2][2], B1[2][2];
;     const char* cA = (const char*)g.A + (size_t)cur.pm * tstepA; const char* cB = (const char*)g.Bt + (size_t)cur.pn * tstepB;
;     S.a_ready(cur);
;     PG8_STAGE(PG8_SB(0, 0), cB, voffB); PG8_STAGE(PG8_SA(0, 0), cA, voffA); PG8_STAGE(PG8_SB(0, 1), cB + hstepB, voffB); PG8_STAGE(PG8_SA(0, 1), cA + hstepA, voffA);
;     if (wr == 1) PG8_BAR;
;     PG8_WAIT_V(4); PG8_BAR;
;     PG8_STAGE(PG8_SB(1, 0), cB + kstep, voffB); PG8_STAGE(PG8_SA(1, 0), cA + kstepA, voffA); PG8_STAGE(PG8_SB(1, 1), cB + hstepB + kstep, voffB);
;     PG8_WAIT_V(6); PG8_BAR;
;     __device__ __forceinline__ void operator()(const f32x4 (&acc)[2][2][4][2], const Unit& u, int wr, int wc, int fr, int fq) const {
;     ...
;             for (int m = 0; m < 4; ++m) sq[ai][m] = *(const f32x4*)(ss2 + (size_t)(row0 + ai * 128 + m * 16) * 16 + 4 * fq);
.LBB0_717:
	s_add_u32 s2, s0, 0xcc00000
	s_addc_u32 s3, s1, 0
	s_lshl_b32 s35, s4, 6
	s_lshl_b32 s7, s4, 13
	s_lshl_b32 s10, s5, 5
	s_mov_b64 s[4:5], 0x80
	s_and_b32 s36, s10, 0x60
	s_add_i32 m0, s28, 0x18000
	v_lshl_add_u64 v[6:7], v[6:7], 0, s[4:5]
	s_lshl_b32 s11, s36, 7
	s_waitcnt vmcnt(4)
	s_barrier
	global_load_lds_dwordx4 v[6:7], off
	v_lshl_add_u64 v[4:5], v[4:5], 0, s[4:5]
	s_add_i32 m0, s28, 0x1a000
	s_add_i32 s37, s28, 0x8000
	s_add_i32 s38, s28, 0xa000
	global_load_lds_dwordx4 v[4:5], off
	v_lshl_add_u64 v[2:3], v[2:3], 0, s[4:5]
	s_mov_b32 m0, s37
	s_add_u32 s8, s18, 0x40080
	global_load_lds_dwordx4 v[2:3], off
	v_lshl_add_u64 v[0:1], v[0:1], 0, s[4:5]
	s_mov_b32 m0, s38
	s_addc_u32 s9, s19, 0
	global_load_lds_dwordx4 v[0:1], off
	s_add_i32 m0, s28, 0x1c000
	v_lshl_add_u64 v[0:1], s[8:9], 0, v[150:151]
	global_load_lds_dwordx4 v[0:1], off
	v_lshl_add_u64 v[0:1], s[8:9], 0, v[154:155]
	s_add_i32 m0, s28, 0x1e000
	v_and_b32_e32 v172, 15, v8
	global_load_lds_dwordx4 v[0:1], off
	v_bfe_u32 v2, v8, 4, 2
	v_lshlrev_b32_e32 v156, 4, v2
	v_lshlrev_b32_e32 v4, 2, v172
	v_lshl_or_b32 v0, v172, 6, v156
	v_and_b32_e32 v1, 32, v4
	v_bitop3_b32 v5, v0, s7, v1 bitop3:0xde
	v_bitop3_b32 v173, v0, s11, v1 bitop3:0xde
	v_lshl_add_u64 v[0:1], s[0:1], 0, v[156:157]
	s_mov_b64 s[0:1], 0x3100000
	v_lshl_add_u64 v[158:159], v[0:1], 0, s[0:1]
	v_lshlrev_b32_e32 v1, 14, v9
	v_and_b32_e32 v1, 0xffff8000, v1
	v_lshlrev_b32_e32 v3, 3, v2
	v_lshlrev_b32_e32 v0, 6, v2
	v_lshl_add_u32 v1, v10, 11, v1
	v_and_b32_e32 v2, 1, v9
	v_lshl_or_b32 v1, v2, 6, v1
	v_lshl_add_u32 v160, v11, 1, v1
	v_lshlrev_b32_e32 v1, 14, v12
	v_and_b32_e32 v1, 0xffff8000, v1
	s_waitcnt vmcnt(6)
	s_movk_i32 s0, 0x80
	v_lshl_add_u32 v1, v13, 11, v1
	v_and_b32_e32 v2, 1, v12
	v_bitop3_b32 v174, v0, 64, v4 bitop3:0x36
	v_bitop3_b32 v175, v0, s0, v4 bitop3:0x36
	v_and_or_b32 v0, s10, 32, v3
	v_lshl_or_b32 v1, v2, 6, v1
	s_add_i32 s39, 0, 0x10000
	s_add_i32 s40, 0, 0x14000
	s_sext_i32_i8 s15, s6
	v_mov_b32_e32 v161, v157
	v_lshl_add_u32 v162, v14, 1, v1
	v_mov_b32_e32 v163, v157
	v_mov_b64_e32 v[164:165], 0x800
	v_mov_b64_e32 v[166:167], 0x7ff
	v_add_u32_e32 v176, s39, v173
	v_add_u32_e32 v177, 0, v5
	v_add_u32_e32 v180, s40, v173
	v_mov_b32_e32 v181, 0x358637bd
	s_mov_b32 s41, 0x800000
	v_lshlrev_b32_e32 v168, 1, v0
	s_barrier
	s_lshl_b32 s70, s14, 8
	s_add_i32 s70, s70, s35
	v_or_b32_e32 v248, s70, v172
	v_ashrrev_i32_e32 v249, 31, v248
	v_lshlrev_b64 v[248:249], 6, v[248:249]
	v_lshl_add_u64 v[248:249], v[158:159], 0, v[248:249]
	global_load_dwordx4 v[232:235], v[248:249], off
	global_load_dwordx4 v[236:239], v[248:249], off offset:1024
	global_load_dwordx4 v[240:243], v[248:249], off offset:2048
	global_load_dwordx4 v[244:247], v[248:249], off offset:3072

; #define PG8_STAGE(bufoff, gbase, voff) do { _Pragma("unroll") for (int _i = 0; _i < 2; ++_i) \
;         __builtin_amdgcn_global_load_lds((const unsigned*)((const char*)(gbase) + (voff)[_i]), (LAS unsigned*)(lds + (bufoff) + ldsw + _i * 8192), 16, 0, 0); } while (0)
; #define PG8_LDA(dst, b, h) do { _Pragma("unroll") for (int m = 0; m < 4; ++m) _Pragma("unroll") for (int k = 0; k < 2; ++k) dst[m][k] = *(const LAS bf16x8*)(lds + PG8_SA(b, h) + aoff + m * 2048 + k * 1024); } while (0)
; #define PG8_WAIT_V(n) asm volatile("s_waitcnt vmcnt(" #n ")" ::: "memory")
; template <class Epi, class Sched>
; __device__ __forceinline__ void gemm_phase(const int wv, LAS unsigned char* lds, const Gemm g, const Sched& S, const Epi& E) {
;     ...
;         for (int t = 0; t < nt; t += 2) {
;             const bool last = (t == nt - 2);
;             const char* a1 = cA + (size_t)(t + 1) * kstepA;
;             const char* a2 = last ? nA : cA + (size_t)(t + 2) * kstepA; const char* b2 = last ? nB : cB + (size_t)(t + 2) * kstep;
;             const char* a3 = a2 + kstepA; const char* b3 = b2 + kstep;
;             if (last && has_next) S.a_ready(nxt);
;             PG8_LDB(B0, 0, 0); PG8_SCHED; PG8_LDA(At, 0, 0); PG8_STAGE(PG8_SA(1, 1), a1 + hstepA, voffA);
;             PG8_WAIT_L(8); PG8_BAR; PG8_WAIT_L(0); PG8_MMA(0, 0, At, B0); PG8_BAR; PG8_SCHED;
;             PG8_LDB(B1, 0, 1); PG8_STAGE(PG8_SB(0, 0), b2, voffB);
;             PG8_BAR; PG8_WAIT_L(0); PG8_MMA(0, 1, At, B1); PG8_BAR;
;             PG8_LDA(At, 0, 1); PG8_STAGE(PG8_SA(0, 0), a2, voffA);
;             PG8_BAR; PG8_WAIT_L(0); PG8_MMA(1, 0, At, B0); PG8_BAR; PG8_SCHED;
;             PG8_STAGE(PG8_SB(0, 1), b2 + hstepB, voffB);
;             PG8_WAIT_V(6); PG8_BAR; PG8_MMA(1, 1, At, B1); PG8_BAR;
;             PG8_LDB(B0, 1, 0); PG8_SCHED; PG8_LDA(At, 1, 0); PG8_STAGE(PG8_SA(0, 1), a2 + hstepA, voffA);
;             PG8_WAIT_L(8); PG8_BAR; PG8_WAIT_L(0); PG8_MMA(0, 0, At, B0); PG8_BAR; PG8_SCHED;
;             PG8_LDB(B1, 1, 1); PG8_STAGE(PG8_SB(1, 0), b3, voffB);
;             PG8_BAR; PG8_WAIT_L(0); PG8_MMA(0, 1, At, B1); PG8_BAR;
;             PG8_LDA(At, 1, 1); PG8_STAGE(PG8_SA(1, 0), a3, voffA);
;             PG8_BAR; PG8_WAIT_L(0); PG8_MMA(1, 0, At, B0); PG8_BAR; PG8_SCHED;
;             PG8_STAGE(PG8_SB(1, 1), b3 + hstepB, voffB);
;             PG8_WAIT_V(6); PG8_BAR; PG8_MMA(1, 1, At, B1); PG8_BAR;
;         }
.LBB0_725:
	ds_read_b128 v[128:131], v176
	ds_read_b128 v[132:135], v176 offset:1024
	ds_read_b128 v[136:139], v176 offset:2048
	ds_read_b128 v[140:143], v176 offset:3072
	s_add_u32 s18, s16, 0xfffc0080
	s_addc_u32 s19, s17, -1
	s_cmp_eq_u32 s46, 12
	s_cselect_b32 s21, s9, s19
	s_cselect_b32 s20, s42, s18
	s_cselect_b32 s19, s7, s45
	s_cselect_b32 s18, s43, s44
	v_lshl_add_u64 v[170:171], s[16:17], 0, v[160:161]
	s_add_i32 m0, s28, 0xc000
	ds_read_b128 v[144:147], v177
	ds_read_b128 v[182:185], v177 offset:1024
	ds_read_b128 v[186:189], v177 offset:2048
	ds_read_b128 v[190:193], v177 offset:3072
	ds_read_b128 v[194:197], v177 offset:4096
	ds_read_b128 v[198:201], v177 offset:5120
	ds_read_b128 v[202:205], v177 offset:6144
	ds_read_b128 v[206:209], v177 offset:7168
	global_load_lds_dwordx4 v[170:171], off
	s_add_i32 m0, s28, 0xe000
	v_lshl_add_u64 v[170:171], s[16:17], 0, v[162:163]
	global_load_lds_dwordx4 v[170:171], off
	s_waitcnt lgkmcnt(8)
	s_barrier
	s_waitcnt lgkmcnt(0)
	v_mfma_f32_16x16x32_bf16 v[124:127], v[128:131], v[144:147], v[124:127]
	v_mfma_f32_16x16x32_bf16 v[120:123], v[136:139], v[144:147], v[120:123]
	v_mfma_f32_16x16x32_bf16 v[108:111], v[128:131], v[186:189], v[108:111]
	v_mfma_f32_16x16x32_bf16 v[104:107], v[136:139], v[186:189], v[104:107]
	v_mfma_f32_16x16x32_bf16 v[92:95], v[128:131], v[194:197], v[92:95]
	v_mfma_f32_16x16x32_bf16 v[88:91], v[136:139], v[194:197], v[88:91]
	v_mfma_f32_16x16x32_bf16 v[76:79], v[128:131], v[202:205], v[76:79]
	v_mfma_f32_16x16x32_bf16 v[72:75], v[136:139], v[202:205], v[72:75]
	v_mfma_f32_16x16x32_bf16 v[124:127], v[132:135], v[182:185], v[124:127]
	v_mfma_f32_16x16x32_bf16 v[120:123], v[140:143], v[182:185], v[120:123]
	v_mfma_f32_16x16x32_bf16 v[108:111], v[132:135], v[190:193], v[108:111]
	v_mfma_f32_16x16x32_bf16 v[104:107], v[140:143], v[190:193], v[104:107]
	v_mfma_f32_16x16x32_bf16 v[92:95], v[132:135], v[198:201], v[92:95]
	v_mfma_f32_16x16x32_bf16 v[88:91], v[140:143], v[198:201], v[88:91]
	v_mfma_f32_16x16x32_bf16 v[76:79], v[132:135], v[206:209], v[76:79]
	v_mfma_f32_16x16x32_bf16 v[72:75], v[140:143], v[206:209], v[72:75]
	s_barrier
	s_add_i32 s47, s39, s27
	v_lshl_add_u64 v[170:171], s[18:19], 0, v[150:151]
	s_mov_b32 m0, s47
	ds_read_b128 v[210:213], v180
	ds_read_b128 v[214:217], v180 offset:1024
	ds_read_b128 v[218:221], v180 offset:2048
	ds_read_b128 v[222:225], v180 offset:3072
	global_load_lds_dwordx4 v[170:171], off
	s_add_i32 m0, s47, 0x2000
	v_lshl_add_u64 v[226:227], s[18:19], 0, v[154:155]
	global_load_lds_dwordx4 v[226:227], off
	s_barrier
	s_waitcnt lgkmcnt(0)
	v_mfma_f32_16x16x32_bf16 v[116:119], v[210:213], v[144:147], v[116:119]
	v_mfma_f32_16x16x32_bf16 v[112:115], v[218:221], v[144:147], v[112:115]
	v_mfma_f32_16x16x32_bf16 v[100:103], v[210:213], v[186:189], v[100:103]
	v_mfma_f32_16x16x32_bf16 v[96:99], v[218:221], v[186:189], v[96:99]
	v_mfma_f32_16x16x32_bf16 v[84:87], v[210:213], v[194:197], v[84:87]
	v_mfma_f32_16x16x32_bf16 v[80:83], v[218:221], v[194:197], v[80:83]
	v_mfma_f32_16x16x32_bf16 v[68:71], v[210:213], v[202:205], v[68:71]
	v_mfma_f32_16x16x32_bf16 v[64:67], v[218:221], v[202:205], v[64:67]
	v_mfma_f32_16x16x32_bf16 v[116:119], v[214:217], v[182:185], v[116:119]
	v_mfma_f32_16x16x32_bf16 v[112:115], v[222:225], v[182:185], v[112:115]
	v_mfma_f32_16x16x32_bf16 v[100:103], v[214:217], v[190:193], v[100:103]
	v_mfma_f32_16x16x32_bf16 v[96:99], v[222:225], v[190:193], v[96:99]
	v_mfma_f32_16x16x32_bf16 v[84:87], v[214:217], v[198:201], v[84:87]
	v_mfma_f32_16x16x32_bf16 v[80:83], v[222:225], v[198:201], v[80:83]
	v_mfma_f32_16x16x32_bf16 v[68:71], v[214:217], v[206:209], v[68:71]
	v_mfma_f32_16x16x32_bf16 v[64:67], v[222:225], v[206:209], v[64:67]
	s_mov_b32 m0, s28
	v_lshl_add_u64 v[228:229], s[20:21], 0, v[148:149]
	s_barrier
	ds_read_b128 v[144:147], v177 offset:16384
	ds_read_b128 v[182:185], v177 offset:17408
	ds_read_b128 v[186:189], v177 offset:18432
	ds_read_b128 v[190:193], v177 offset:19456
	ds_read_b128 v[194:197], v177 offset:20480
	ds_read_b128 v[198:201], v177 offset:21504
	ds_read_b128 v[202:205], v177 offset:22528
	ds_read_b128 v[206:209], v177 offset:23552
	global_load_lds_dwordx4 v[228:229], off
	s_mov_b32 m0, s29
	v_lshl_add_u64 v[230:231], s[20:21], 0, v[152:153]
	global_load_lds_dwordx4 v[230:231], off
	s_barrier
	s_waitcnt lgkmcnt(0)
	v_mfma_f32_16x16x32_bf16 v[60:63], v[128:131], v[144:147], v[60:63]
	v_mfma_f32_16x16x32_bf16 v[56:59], v[136:139], v[144:147], v[56:59]
	v_mfma_f32_16x16x32_bf16 v[44:47], v[128:131], v[186:189], v[44:47]
	v_mfma_f32_16x16x32_bf16 v[40:43], v[136:139], v[186:189], v[40:43]
	v_mfma_f32_16x16x32_bf16 v[28:31], v[128:131], v[194:197], v[28:31]
	v_mfma_f32_16x16x32_bf16 v[24:27], v[136:139], v[194:197], v[24:27]
	v_mfma_f32_16x16x32_bf16 v[12:15], v[128:131], v[202:205], v[12:15]
	v_mfma_f32_16x16x32_bf16 v[8:11], v[136:139], v[202:205], v[8:11]
	v_mfma_f32_16x16x32_bf16 v[60:63], v[132:135], v[182:185], v[60:63]
	v_mfma_f32_16x16x32_bf16 v[56:59], v[140:143], v[182:185], v[56:59]
	v_mfma_f32_16x16x32_bf16 v[44:47], v[132:135], v[190:193], v[44:47]
	v_mfma_f32_16x16x32_bf16 v[40:43], v[140:143], v[190:193], v[40:43]
	v_mfma_f32_16x16x32_bf16 v[28:31], v[132:135], v[198:201], v[28:31]
	v_mfma_f32_16x16x32_bf16 v[24:27], v[140:143], v[198:201], v[24:27]
	v_mfma_f32_16x16x32_bf16 v[12:15], v[132:135], v[206:209], v[12:15]
	v_mfma_f32_16x16x32_bf16 v[8:11], v[140:143], v[206:209], v[8:11]
	s_barrier
	s_add_u32 s48, s18, 0x40000
	s_addc_u32 s49, s19, 0
	s_add_i32 s47, s40, s27
	s_mov_b32 m0, s47
	v_lshl_add_u64 v[128:129], s[48:49], 0, v[150:151]
	global_load_lds_dwordx4 v[128:129], off
	s_add_i32 m0, s47, 0x2000
	v_lshl_add_u64 v[128:129], s[48:49], 0, v[154:155]
	global_load_lds_dwordx4 v[128:129], off
	s_waitcnt vmcnt(6)
	s_barrier
; #define PG8_STAGE(bufoff, gbase, voff) do { _Pragma("unroll") for (int _i = 0; _i < 2; ++_i) \
;         __builtin_amdgcn_global_load_lds((const unsigned*)((const char*)(gbase) + (voff)[_i]), (LAS unsigned*)(lds + (bufoff) + ldsw + _i * 8192), 16, 0, 0); } while (0)
; #define PG8_LDA(dst, b, h) do { _Pragma("unroll") for (int m = 0; m < 4; ++m) _Pragma("unroll") for (int k = 0; k < 2; ++k) dst[m][k] = *(const LAS bf16x8*)(lds + PG8_SA(b, h) + aoff + m * 2048 + k * 1024); } while (0)
; #define PG8_WAIT_V(n) asm volatile("s_waitcnt vmcnt(" #n ")" ::: "memory")
; template <class Epi, class Sched>
; __device__ __forceinline__ void gemm_phase(const int wv, LAS unsigned char* lds, const Gemm g, const Sched& S, const Epi& E) {
;     ...
;         for (int t = 0; t < nt; t += 2) {
;             const bool last = (t == nt - 2);
;             const char* a1 = cA + (size_t)(t + 1) * kstepA;
;             const char* a2 = last ? nA : cA + (size_t)(t + 2) * kstepA; const char* b2 = last ? nB : cB + (size_t)(t + 2) * kstep;
;             const char* a3 = a2 + kstepA; const char* b3 = b2 + kstep;
;             if (last && has_next) S.a_ready(nxt);
;             PG8_LDB(B0, 0, 0); PG8_SCHED; PG8_LDA(At, 0, 0); PG8_STAGE(PG8_SA(1, 1), a1 + hstepA, voffA);
;             PG8_WAIT_L(8); PG8_BAR; PG8_WAIT_L(0); PG8_MMA(0, 0, At, B0); PG8_BAR; PG8_SCHED;
;             PG8_LDB(B1, 0, 1); PG8_STAGE(PG8_SB(0, 0), b2, voffB);
;             PG8_BAR; PG8_WAIT_L(0); PG8_MMA(0, 1, At, B1); PG8_BAR;
;             PG8_LDA(At, 0, 1); PG8_STAGE(PG8_SA(0, 0), a2, voffA);
;             PG8_BAR; PG8_WAIT_L(0); PG8_MMA(1, 0, At, B0); PG8_BAR; PG8_SCHED;
;             PG8_STAGE(PG8_SB(0, 1), b2 + hstepB, voffB);
;             PG8_WAIT_V(6); PG8_BAR; PG8_MMA(1, 1, At, B1); PG8_BAR;
;             PG8_LDB(B0, 1, 0); PG8_SCHED; PG8_LDA(At, 1, 0); PG8_STAGE(PG8_SA(0, 1), a2 + hstepA, voffA);
;             PG8_WAIT_L(8); PG8_BAR; PG8_WAIT_L(0); PG8_MMA(0, 0, At, B0); PG8_BAR; PG8_SCHED;
;             PG8_LDB(B1, 1, 1); PG8_STAGE(PG8_SB(1, 0), b3, voffB);
;             PG8_BAR; PG8_WAIT_L(0); PG8_MMA(0, 1, At, B1); PG8_BAR;
;             PG8_LDA(At, 1, 1); PG8_STAGE(PG8_SA(1, 0), a3, voffA);
;             PG8_BAR; PG8_WAIT_L(0); PG8_MMA(1, 0, At, B0); PG8_BAR; PG8_SCHED;
;             PG8_STAGE(PG8_SB(1, 1), b3 + hstepB, voffB);
;             PG8_WAIT_V(6); PG8_BAR; PG8_MMA(1, 1, At, B1); PG8_BAR;
;         }
	v_mfma_f32_16x16x32_bf16 v[52:55], v[210:213], v[144:147], v[52:55]
	v_mfma_f32_16x16x32_bf16 v[48:51], v[218:221], v[144:147], v[48:51]
	v_mfma_f32_16x16x32_bf16 v[36:39], v[210:213], v[186:189], v[36:39]
	v_mfma_f32_16x16x32_bf16 v[32:35], v[218:221], v[186:189], v[32:35]
	v_mfma_f32_16x16x32_bf16 v[20:23], v[210:213], v[194:197], v[20:23]
	v_mfma_f32_16x16x32_bf16 v[16:19], v[218:221], v[194:197], v[16:19]
	v_mfma_f32_16x16x32_bf16 v[4:7], v[210:213], v[202:205], v[4:7]
	v_mfma_f32_16x16x32_bf16 v[0:3], v[218:221], v[202:205], v[0:3]
	v_mfma_f32_16x16x32_bf16 v[52:55], v[214:217], v[182:185], v[52:55]
	v_mfma_f32_16x16x32_bf16 v[48:51], v[222:225], v[182:185], v[48:51]
	v_mfma_f32_16x16x32_bf16 v[36:39], v[214:217], v[190:193], v[36:39]
	v_mfma_f32_16x16x32_bf16 v[32:35], v[222:225], v[190:193], v[32:35]
	v_mfma_f32_16x16x32_bf16 v[20:23], v[214:217], v[198:201], v[20:23]
	v_mfma_f32_16x16x32_bf16 v[16:19], v[222:225], v[198:201], v[16:19]
	v_mfma_f32_16x16x32_bf16 v[4:7], v[214:217], v[206:209], v[4:7]
	v_mfma_f32_16x16x32_bf16 v[0:3], v[222:225], v[206:209], v[0:3]
	s_add_i32 s47, 0, 0x18000
	v_add_u32_e32 v140, s47, v173
	s_barrier
	ds_read_b128 v[128:131], v140
	ds_read_b128 v[132:135], v140 offset:1024
	ds_read_b128 v[136:139], v140 offset:2048
	ds_read_b128 v[140:143], v140 offset:3072
	s_add_u32 s20, s20, 0x40000
	s_addc_u32 s21, s21, 0
	s_mov_b32 m0, s30
	v_lshl_add_u64 v[210:211], s[20:21], 0, v[148:149]
	ds_read_b128 v[144:147], v177 offset:32768
	ds_read_b128 v[182:185], v177 offset:33792
	ds_read_b128 v[186:189], v177 offset:34816
	ds_read_b128 v[190:193], v177 offset:35840
	ds_read_b128 v[194:197], v177 offset:36864
	ds_read_b128 v[198:201], v177 offset:37888
	ds_read_b128 v[202:205], v177 offset:38912
	ds_read_b128 v[206:209], v177 offset:39936
	global_load_lds_dwordx4 v[210:211], off
	s_mov_b32 m0, s31
	v_lshl_add_u64 v[210:211], s[20:21], 0, v[152:153]
	global_load_lds_dwordx4 v[210:211], off
	s_waitcnt lgkmcnt(8)
	s_barrier
	s_waitcnt lgkmcnt(0)
	v_mfma_f32_16x16x32_bf16 v[124:127], v[128:131], v[144:147], v[124:127]
	v_mfma_f32_16x16x32_bf16 v[120:123], v[136:139], v[144:147], v[120:123]
	v_mfma_f32_16x16x32_bf16 v[108:111], v[128:131], v[186:189], v[108:111]
	v_mfma_f32_16x16x32_bf16 v[104:107], v[136:139], v[186:189], v[104:107]
	v_mfma_f32_16x16x32_bf16 v[92:95], v[128:131], v[194:197], v[92:95]
	v_mfma_f32_16x16x32_bf16 v[88:91], v[136:139], v[194:197], v[88:91]
	v_mfma_f32_16x16x32_bf16 v[76:79], v[128:131], v[202:205], v[76:79]
	v_mfma_f32_16x16x32_bf16 v[72:75], v[136:139], v[202:205], v[72:75]
	v_mfma_f32_16x16x32_bf16 v[124:127], v[132:135], v[182:185], v[124:127]
	v_mfma_f32_16x16x32_bf16 v[120:123], v[140:143], v[182:185], v[120:123]
	v_mfma_f32_16x16x32_bf16 v[108:111], v[132:135], v[190:193], v[108:111]
	v_mfma_f32_16x16x32_bf16 v[104:107], v[140:143], v[190:193], v[104:107]
	v_mfma_f32_16x16x32_bf16 v[92:95], v[132:135], v[198:201], v[92:95]
	v_mfma_f32_16x16x32_bf16 v[88:91], v[140:143], v[198:201], v[88:91]
	v_mfma_f32_16x16x32_bf16 v[76:79], v[132:135], v[206:209], v[76:79]
	v_mfma_f32_16x16x32_bf16 v[72:75], v[140:143], v[206:209], v[72:75]
	s_barrier
	s_add_i32 s20, 0, 0x1c000
	s_add_i32 s21, s47, s27
	v_add_u32_e32 v156, s20, v173
	v_lshl_add_u64 v[170:171], v[170:171], 0, s[4:5]
	s_mov_b32 m0, s21
	ds_read_b128 v[210:213], v156
	ds_read_b128 v[214:217], v156 offset:1024
	ds_read_b128 v[218:221], v156 offset:2048
	ds_read_b128 v[222:225], v156 offset:3072
	global_load_lds_dwordx4 v[170:171], off
	s_add_i32 m0, s21, 0x2000
	v_lshl_add_u64 v[170:171], v[226:227], 0, s[4:5]
	global_load_lds_dwordx4 v[170:171], off
	s_barrier
	s_waitcnt lgkmcnt(0)
	v_mfma_f32_16x16x32_bf16 v[116:119], v[210:213], v[144:147], v[116:119]
	v_mfma_f32_16x16x32_bf16 v[112:115], v[218:221], v[144:147], v[112:115]
	v_mfma_f32_16x16x32_bf16 v[100:103], v[210:213], v[186:189], v[100:103]
	v_mfma_f32_16x16x32_bf16 v[96:99], v[218:221], v[186:189], v[96:99]
	v_mfma_f32_16x16x32_bf16 v[84:87], v[210:213], v[194:197], v[84:87]
	v_mfma_f32_16x16x32_bf16 v[80:83], v[218:221], v[194:197], v[80:83]
	v_mfma_f32_16x16x32_bf16 v[68:71], v[210:213], v[202:205], v[68:71]
	v_mfma_f32_16x16x32_bf16 v[64:67], v[218:221], v[202:205], v[64:67]
	v_mfma_f32_16x16x32_bf16 v[116:119], v[214:217], v[182:185], v[116:119]
	v_mfma_f32_16x16x32_bf16 v[112:115], v[222:225], v[182:185], v[112:115]
	v_mfma_f32_16x16x32_bf16 v[100:103], v[214:217], v[190:193], v[100:103]
	v_mfma_f32_16x16x32_bf16 v[96:99], v[222:225], v[190:193], v[96:99]
	v_mfma_f32_16x16x32_bf16 v[84:87], v[214:217], v[198:201], v[84:87]
	v_mfma_f32_16x16x32_bf16 v[80:83], v[222:225], v[198:201], v[80:83]
	v_mfma_f32_16x16x32_bf16 v[68:71], v[214:217], v[206:209], v[68:71]
	v_mfma_f32_16x16x32_bf16 v[64:67], v[222:225], v[206:209], v[64:67]
	s_mov_b32 m0, s37
	v_lshl_add_u64 v[170:171], v[228:229], 0, s[4:5]
	s_barrier
	ds_read_b128 v[144:147], v177 offset:49152
	ds_read_b128 v[182:185], v177 offset:50176
	ds_read_b128 v[186:189], v177 offset:51200
	ds_read_b128 v[190:193], v177 offset:52224
	ds_read_b128 v[194:197], v177 offset:53248
	ds_read_b128 v[198:201], v177 offset:54272
	ds_read_b128 v[202:205], v177 offset:55296
	ds_read_b128 v[206:209], v177 offset:56320
	global_load_lds_dwordx4 v[170:171], off
	s_mov_b32 m0, s38
	v_lshl_add_u64 v[170:171], v[230:231], 0, s[4:5]
	global_load_lds_dwordx4 v[170:171], off
	s_barrier
; #define PG8_WAIT_V(n) asm volatile("s_waitcnt vmcnt(" #n ")" ::: "memory")
; template <class Epi, class Sched>
; __device__ __forceinline__ void gemm_phase(const int wv, LAS unsigned char* lds, const Gemm g, const Sched& S, const Epi& E) {
;     ...
;         for (int t = 0; t < nt; t += 2) {
;             const bool last = (t == nt - 2);
;             const char* a1 = cA + (size_t)(t + 1) * kstepA;
;             const char* a2 = last ? nA : cA + (size_t)(t + 2) * kstepA; const char* b2 = last ? nB : cB + (size_t)(t + 2) * kstep;
;             const char* a3 = a2 + kstepA; const char* b3 = b2 + kstep;
;             if (last && has_next) S.a_ready(nxt);
;             PG8_LDB(B0, 0, 0); PG8_SCHED; PG8_LDA(At, 0, 0); PG8_STAGE(PG8_SA(1, 1), a1 + hstepA, voffA);
;             PG8_WAIT_L(8); PG8_BAR; PG8_WAIT_L(0); PG8_MMA(0, 0, At, B0); PG8_BAR; PG8_SCHED;
;             PG8_LDB(B1, 0, 1); PG8_STAGE(PG8_SB(0, 0), b2, voffB);
;             PG8_BAR; PG8_WAIT_L(0); PG8_MMA(0, 1, At, B1); PG8_BAR;
;             PG8_LDA(At, 0, 1); PG8_STAGE(PG8_SA(0, 0), a2, voffA);
;             PG8_BAR; PG8_WAIT_L(0); PG8_MMA(1, 0, At, B0); PG8_BAR; PG8_SCHED;
;             PG8_STAGE(PG8_SB(0, 1), b2 + hstepB, voffB);
;             PG8_WAIT_V(6); PG8_BAR; PG8_MMA(1, 1, At, B1); PG8_BAR;
;             PG8_LDB(B0, 1, 0); PG8_SCHED; PG8_LDA(At, 1, 0); PG8_STAGE(PG8_SA(0, 1), a2 + hstepA, voffA);
;             PG8_WAIT_L(8); PG8_BAR; PG8_WAIT_L(0); PG8_MMA(0, 0, At, B0); PG8_BAR; PG8_SCHED;
;             PG8_LDB(B1, 1, 1); PG8_STAGE(PG8_SB(1, 0), b3, voffB);
;             PG8_BAR; PG8_WAIT_L(0); PG8_MMA(0, 1, At, B1); PG8_BAR;
;             PG8_LDA(At, 1, 1); PG8_STAGE(PG8_SA(1, 0), a3, voffA);
;             PG8_BAR; PG8_WAIT_L(0); PG8_MMA(1, 0, At, B0); PG8_BAR; PG8_SCHED;
;             PG8_STAGE(PG8_SB(1, 1), b3 + hstepB, voffB);
;             PG8_WAIT_V(6); PG8_BAR; PG8_MMA(1, 1, At, B1); PG8_BAR;
;         }
;     __device__ __forceinline__ void operator()(const f32x4 (&acc)[2][2][4][2], const Unit& u, int wr, int wc, int fr, int fq) const {
;         const int row0 = u.pm * 256 + wr * 64 + fr; const int col0 = u.pn * 256 + wc * 32 + 8 * fq;
;         f32x4 sq[2][4];
; #pragma unroll
;         for (int ai = 0; ai < 2; ++ai)
; #pragma unroll
;             for (int m = 0; m < 4; ++m) sq[ai][m] = *(const f32x4*)(ss2 + (size_t)(row0 + ai * 128 + m * 16) * 16 + 4 * fq);
	s_waitcnt lgkmcnt(0)
	v_mfma_f32_16x16x32_bf16 v[60:63], v[128:131], v[144:147], v[60:63]
	v_mfma_f32_16x16x32_bf16 v[56:59], v[136:139], v[144:147], v[56:59]
	v_mfma_f32_16x16x32_bf16 v[44:47], v[128:131], v[186:189], v[44:47]
	v_mfma_f32_16x16x32_bf16 v[40:43], v[136:139], v[186:189], v[40:43]
	v_mfma_f32_16x16x32_bf16 v[28:31], v[128:131], v[194:197], v[28:31]
	v_mfma_f32_16x16x32_bf16 v[24:27], v[136:139], v[194:197], v[24:27]
	v_mfma_f32_16x16x32_bf16 v[12:15], v[128:131], v[202:205], v[12:15]
	v_mfma_f32_16x16x32_bf16 v[8:11], v[136:139], v[202:205], v[8:11]
	v_mfma_f32_16x16x32_bf16 v[60:63], v[132:135], v[182:185], v[60:63]
	v_mfma_f32_16x16x32_bf16 v[56:59], v[140:143], v[182:185], v[56:59]
	v_mfma_f32_16x16x32_bf16 v[44:47], v[132:135], v[190:193], v[44:47]
	v_mfma_f32_16x16x32_bf16 v[40:43], v[140:143], v[190:193], v[40:43]
	v_mfma_f32_16x16x32_bf16 v[28:31], v[132:135], v[198:201], v[28:31]
	v_mfma_f32_16x16x32_bf16 v[24:27], v[140:143], v[198:201], v[24:27]
	v_mfma_f32_16x16x32_bf16 v[12:15], v[132:135], v[206:209], v[12:15]
	v_mfma_f32_16x16x32_bf16 v[8:11], v[140:143], v[206:209], v[8:11]
	s_barrier
	s_add_u32 s18, s18, 0x40080
	s_addc_u32 s19, s19, 0
	s_add_i32 s20, s20, s27
	s_mov_b32 m0, s20
	v_lshl_add_u64 v[128:129], s[18:19], 0, v[150:151]
	global_load_lds_dwordx4 v[128:129], off
	s_add_i32 m0, s20, 0x2000
	v_lshl_add_u64 v[128:129], s[18:19], 0, v[154:155]
	global_load_lds_dwordx4 v[128:129], off
	s_waitcnt vmcnt(6)
	s_barrier
	v_mfma_f32_16x16x32_bf16 v[52:55], v[210:213], v[144:147], v[52:55]
	v_mfma_f32_16x16x32_bf16 v[48:51], v[218:221], v[144:147], v[48:51]
	v_mfma_f32_16x16x32_bf16 v[36:39], v[210:213], v[186:189], v[36:39]
	v_mfma_f32_16x16x32_bf16 v[32:35], v[218:221], v[186:189], v[32:35]
	v_mfma_f32_16x16x32_bf16 v[20:23], v[210:213], v[194:197], v[20:23]
	v_mfma_f32_16x16x32_bf16 v[16:19], v[218:221], v[194:197], v[16:19]
	v_mfma_f32_16x16x32_bf16 v[4:7], v[210:213], v[202:205], v[4:7]
	v_mfma_f32_16x16x32_bf16 v[0:3], v[218:221], v[202:205], v[0:3]
	v_mfma_f32_16x16x32_bf16 v[52:55], v[214:217], v[182:185], v[52:55]
	v_mfma_f32_16x16x32_bf16 v[48:51], v[222:225], v[182:185], v[48:51]
	v_mfma_f32_16x16x32_bf16 v[36:39], v[214:217], v[190:193], v[36:39]
	v_mfma_f32_16x16x32_bf16 v[32:35], v[222:225], v[190:193], v[32:35]
	v_mfma_f32_16x16x32_bf16 v[20:23], v[214:217], v[198:201], v[20:23]
	v_mfma_f32_16x16x32_bf16 v[16:19], v[222:225], v[198:201], v[16:19]
	v_mfma_f32_16x16x32_bf16 v[4:7], v[214:217], v[206:209], v[4:7]
	v_mfma_f32_16x16x32_bf16 v[0:3], v[222:225], v[206:209], v[0:3]
	s_add_i32 s46, s46, 2
	s_add_u32 s16, s16, 0x100
	s_addc_u32 s17, s17, 0
	s_add_u32 s44, s44, 0x100
	s_addc_u32 s45, s45, 0
	s_cmp_gt_u32 s46, 13
	s_barrier
	s_cbranch_scc0 .LBB0_725
	s_lshl_b32 s7, s14, 8
	s_add_i32 s7, s7, s35
	v_or_b32_e32 v132, s7, v172
	v_ashrrev_i32_e32 v133, 31, v132
	v_lshlrev_b64 v[128:129], 6, v[132:133]
	v_lshl_add_u64 v[134:135], v[158:159], 0, v[128:129]
	v_or_b32_e32 v136, 16, v132
	v_ashrrev_i32_e32 v137, 31, v136
	v_lshlrev_b64 v[136:137], 6, v[136:137]
	v_lshl_add_u64 v[136:137], v[158:159], 0, v[136:137]
	v_or_b32_e32 v136, 32, v132
	v_or_b32_e32 v138, 48, v132
	v_add_u32_e32 v170, 0x80, v132
	v_lshlrev_b32_e32 v132, 7, v132
	v_ashrrev_i32_e32 v137, 31, v136
	v_ashrrev_i32_e32 v139, 31, v138
	v_and_b32_e32 v156, 0x6780, v132
	v_lshlrev_b64 v[132:133], 6, v[136:137]
	v_lshlrev_b64 v[136:137], 6, v[138:139]
	v_lshl_add_u64 v[132:133], v[158:159], 0, v[132:133]
	v_lshl_add_u64 v[136:137], v[158:159], 0, v[136:137]
	v_ashrrev_i32_e32 v171, 31, v170
	v_lshlrev_b64 v[138:139], 6, v[170:171]
	v_add_co_u32_e32 v190, vcc, s33, v134
	s_lshl_b32 s9, s15, 8
	s_nop 0
	v_addc_co_u32_e32 v191, vcc, 0, v135, vcc
	s_or_b32 s9, s9, s36
	s_ashr_i32 s14, s7, 2
	s_ashr_i32 s7, s9, 6
	s_and_b32 s16, s14, 0xffffffc0
	s_add_i32 s14, s16, s7
	s_ashr_i32 s15, s14, 31
	s_lshl_b64 s[14:15], s[14:15], 15
	s_add_u32 s14, s2, s14
	v_lshl_add_u64 v[138:139], v[158:159], 0, v[138:139]
	s_addc_u32 s15, s3, s15
	v_mov_b32_e32 v169, v157
	s_or_b32 s9, s7, 2
	s_add_i32 s16, s16, s9
	s_ashr_i32 s17, s16, 31
	s_lshl_b64 s[16:17], s[16:17], 15
	s_add_u32 s16, s2, s16
	s_addc_u32 s17, s3, s17
	s_mov_b64 s[18:19], s[12:13]
	s_waitcnt vmcnt(0)
	v_mov_b32_e32 v128, v232
	v_mov_b32_e32 v129, v233
	v_mov_b32_e32 v130, v234
	v_mov_b32_e32 v131, v235
	v_mov_b32_e32 v182, v236
	v_mov_b32_e32 v183, v237
	v_mov_b32_e32 v184, v238
	v_mov_b32_e32 v185, v239
	v_mov_b32_e32 v186, v240
	v_mov_b32_e32 v187, v241
	v_mov_b32_e32 v188, v242
	v_mov_b32_e32 v189, v243
	v_mov_b32_e32 v144, v244
	v_mov_b32_e32 v145, v245
	v_mov_b32_e32 v146, v246
	v_mov_b32_e32 v147, v247
	s_cmp_lg_u64 s[0:1], 0
	s_cbranch_scc1 .Lup_nopf
	s_lshl_b32 s70, s8, 8
	s_add_i32 s70, s70, s35
	v_or_b32_e32 v248, s70, v172
	v_ashrrev_i32_e32 v249, 31, v248
	v_lshlrev_b64 v[248:249], 6, v[248:249]
	v_lshl_add_u64 v[248:249], v[158:159], 0, v[248:249]
	global_load_dwordx4 v[232:235], v[248:249], off
	global_load_dwordx4 v[236:239], v[248:249], off offset:1024
	global_load_dwordx4 v[240:243], v[248:249], off offset:2048
	global_load_dwordx4 v[244:247], v[248:249], off offset:3072
; __device__ __forceinline__ float shx(float v, int lane, int mask) { return __int_as_float(__builtin_amdgcn_ds_bpermute((lane ^ mask) << 2, __float_as_int(v))); }
; __device__ __forceinline__ unsigned cvt_pk_bf16(float lo, float hi) { unsigned r; asm volatile("v_cvt_pk_bf16_f32 %0, %1, %2" : "=v"(r) : "v"(lo), "v"(hi)); return r; }
;     __device__ __forceinline__ void operator()(const f32x4 (&acc)[2][2][4][2], const Unit& u, int wr, int wc, int fr, int fq) const {
;     ...
; #pragma unroll
;         for (int ai = 0; ai < 2; ++ai)
; #pragma unroll
;             for (int m = 0; m < 4; ++m) {
;                 const int row = row0 + ai * 128 + m * 16;
;                 float ss = (sq[ai][m][0] + sq[ai][m][1]) + (sq[ai][m][2] + sq[ai][m][3]);
;                 ss += shx(ss, fq * 16 + fr, 16); ss += shx(ss, fq * 16 + fr, 32);
;                 const float rs = rsqrtf(ss * (1.0f / 1024.0f) + EPS);
; #pragma unroll
;                 for (int bj = 0; bj < 2; ++bj) {
;                     f32x4 v0 = acc[ai][bj][m][0] * rs, v1 = acc[ai][bj][m][1] * rs;
; #pragma unroll
;                     for (int j = 0; j < 4; ++j) { const float a = fmaxf(v0[j], 0.f), b = fmaxf(v1[j], 0.f); v0[j] = a * a; v1[j] = b * b; }
;                     u32x4 w; w.x = cvt_pk_bf16(v0[0], v0[1]); w.y = cvt_pk_bf16(v0[2], v0[3]); w.z = cvt_pk_bf16(v1[0], v1[1]); w.w = cvt_pk_bf16(v1[2], v1[3]);
;                     { const int col = col0 + bj * 128;
;                       *(u32x4*)(H + ((size_t)((row >> 8) * (DFF / 64) + (col >> 6)) * 256 + (row & 255)) * 64 + (col & 63)) = w; }
;                 }
.Lup_nopf:
	v_mov_b32_e32 v132, v129
	v_mov_b32_e32 v133, v130
	v_mov_b32_e32 v129, v131
	v_pk_add_f32 v[128:129], v[132:133], v[128:129]
	v_mov_b32_e32 v193, v184
	v_add_f32_e32 v171, v128, v129
	ds_bpermute_b32 v192, v174, v171
	global_load_dwordx4 v[140:143], v[138:139], off
	s_nop 0
	global_load_dwordx4 v[136:139], v[190:191], off offset:1024
	global_load_dwordx4 v[132:135], v[190:191], off offset:2048
	global_load_dwordx4 v[128:131], v[190:191], off offset:3072
	v_lshl_add_u64 v[190:191], s[14:15], 0, v[156:157]
	v_lshl_add_u64 v[190:191], v[190:191], 0, v[168:169]
	s_waitcnt lgkmcnt(0)
	v_add_f32_e32 v171, v171, v192
	ds_bpermute_b32 v192, v175, v171
	s_waitcnt lgkmcnt(0)
	v_add_f32_e32 v171, v171, v192
	v_fmamk_f32 v171, v171, 0x3a800000, v181
	v_mul_f32_e32 v192, 0x4b800000, v171
	v_cmp_gt_f32_e32 vcc, s41, v171
	s_nop 1
	v_cndmask_b32_e32 v171, v171, v192, vcc
	v_rsq_f32_e32 v171, v171
	v_mov_b32_e32 v192, v183
	v_mov_b32_e32 v183, v185
	v_mul_f32_e32 v184, 0x45800000, v171
	v_cndmask_b32_e32 v184, v171, v184, vcc
	v_pk_mul_f32 v[126:127], v[126:127], v[184:185] op_sel_hi:[1,0]
	v_pk_mul_f32 v[124:125], v[124:125], v[184:185] op_sel_hi:[1,0]
	v_pk_mul_f32 v[122:123], v[122:123], v[184:185] op_sel_hi:[1,0]
	v_pk_mul_f32 v[120:121], v[120:121], v[184:185] op_sel_hi:[1,0]
	v_pk_mul_f32 v[114:115], v[114:115], v[184:185] op_sel_hi:[1,0]
	v_pk_mul_f32 v[112:113], v[112:113], v[184:185] op_sel_hi:[1,0]
	v_pk_mul_f32 v[116:117], v[116:117], v[184:185] op_sel_hi:[1,0]
	v_max_f32_e32 v124, 0, v124
	v_max_f32_e32 v120, 0, v120
	v_max_f32_e32 v125, 0, v125
	v_max_f32_e32 v121, 0, v121
	v_max_f32_e32 v126, 0, v126
	v_max_f32_e32 v122, 0, v122
	v_max_f32_e32 v127, 0, v127
	v_max_f32_e32 v123, 0, v123
	v_max_f32_e32 v112, 0, v112
	v_max_f32_e32 v113, 0, v113
	v_max_f32_e32 v114, 0, v114
	v_max_f32_e32 v115, 0, v115
	v_pk_mul_f32 v[118:119], v[118:119], v[184:185] op_sel_hi:[1,0]
	v_max_f32_e32 v116, 0, v116
	v_mul_f32_e32 v124, v124, v124
	v_mul_f32_e32 v120, v120, v120
	v_mul_f32_e32 v125, v125, v125
	v_mul_f32_e32 v121, v121, v121
	v_mul_f32_e32 v126, v126, v126
	v_mul_f32_e32 v122, v122, v122
	v_mul_f32_e32 v127, v127, v127
	v_mul_f32_e32 v123, v123, v123
	v_mul_f32_e32 v171, v112, v112
	v_mul_f32_e32 v184, v113, v113
	v_mul_f32_e32 v185, v114, v114
	v_mul_f32_e32 v194, v115, v115
	v_cvt_pk_bf16_f32 v112, v124, v125
	v_cvt_pk_bf16_f32 v113, v126, v127
	v_cvt_pk_bf16_f32 v114, v120, v121
	v_cvt_pk_bf16_f32 v115, v122, v123
	v_max_f32_e32 v117, 0, v117
	v_mul_f32_e32 v116, v116, v116
	global_store_dwordx4 v[190:191], v[112:115], off
	v_mul_f32_e32 v117, v117, v117
	v_max_f32_e32 v118, 0, v118
	v_pk_add_f32 v[114:115], v[192:193], v[182:183]
	v_cvt_pk_bf16_f32 v112, v116, v117
	v_max_f32_e32 v119, 0, v119
	v_add_f32_e32 v116, v114, v115
	ds_bpermute_b32 v117, v174, v116
	v_mul_f32_e32 v118, v118, v118
	v_mul_f32_e32 v119, v119, v119
	v_cvt_pk_bf16_f32 v113, v118, v119
	v_cvt_pk_bf16_f32 v114, v171, v184
	s_waitcnt lgkmcnt(0)
	v_add_f32_e32 v116, v116, v117
	ds_bpermute_b32 v117, v175, v116
	v_cvt_pk_bf16_f32 v115, v185, v194
	s_waitcnt lgkmcnt(0)
	v_add_f32_e32 v116, v116, v117
	v_fmamk_f32 v116, v116, 0x3a800000, v181
	v_mul_f32_e32 v117, 0x4b800000, v116
	v_cmp_gt_f32_e32 vcc, s41, v116
	s_nop 1
	v_cndmask_b32_e32 v116, v116, v117, vcc
	v_rsq_f32_e32 v118, v116
	v_lshl_add_u64 v[116:117], s[16:17], 0, v[156:157]
	v_lshl_add_u64 v[116:117], v[116:117], 0, v[168:169]
	global_store_dwordx4 v[116:117], v[112:115], off
	s_nop 1
	v_mul_f32_e32 v112, 0x45800000, v118
	v_cndmask_b32_e32 v112, v118, v112, vcc
	v_pk_mul_f32 v[104:105], v[104:105], v[112:113] op_sel_hi:[1,0]
	v_pk_mul_f32 v[108:109], v[108:109], v[112:113] op_sel_hi:[1,0]
	v_pk_mul_f32 v[106:107], v[106:107], v[112:113] op_sel_hi:[1,0]
	v_max_f32_e32 v104, 0, v104
	v_pk_mul_f32 v[110:111], v[110:111], v[112:113] op_sel_hi:[1,0]
	v_mul_f32_e32 v113, v104, v104
	v_max_f32_e32 v104, 0, v109
	v_max_f32_e32 v105, 0, v105
	v_max_f32_e32 v106, 0, v106
	v_max_f32_e32 v108, 0, v108
	v_mul_f32_e32 v104, v104, v104
	v_mul_f32_e32 v109, v105, v105
	v_max_f32_e32 v105, 0, v110
	v_mul_f32_e32 v110, v106, v106
	v_max_f32_e32 v106, 0, v111
	v_max_f32_e32 v107, 0, v107
	v_pk_mul_f32 v[96:97], v[96:97], v[112:113] op_sel_hi:[1,0]
	v_mul_f32_e32 v108, v108, v108
	v_mul_f32_e32 v105, v105, v105
	v_mul_f32_e32 v106, v106, v106
	v_mul_f32_e32 v107, v107, v107
	v_cvt_pk_bf16_f32 v104, v108, v104
	v_pk_mul_f32 v[100:101], v[100:101], v[112:113] op_sel_hi:[1,0]
	v_max_f32_e32 v96, 0, v96
	v_cvt_pk_bf16_f32 v105, v105, v106
	v_cvt_pk_bf16_f32 v106, v113, v109
	v_cvt_pk_bf16_f32 v107, v110, v107
	global_store_dwordx4 v[190:191], v[104:107], off offset:2048
	v_max_f32_e32 v97, 0, v97
	v_pk_mul_f32 v[98:99], v[98:99], v[112:113] op_sel_hi:[1,0]
	v_mul_f32_e32 v104, v96, v96
	v_max_f32_e32 v96, 0, v101
	v_mul_f32_e32 v101, v96, v96
	v_mul_f32_e32 v105, v97, v97
	v_mov_b32_e32 v96, v187
	v_mov_b32_e32 v97, v188
	v_mov_b32_e32 v187, v189
	v_pk_add_f32 v[96:97], v[96:97], v[186:187]
	v_pk_mul_f32 v[102:103], v[102:103], v[112:113] op_sel_hi:[1,0]
	v_add_f32_e32 v96, v96, v97
	ds_bpermute_b32 v97, v174, v96
	v_max_f32_e32 v98, 0, v98
	v_mul_f32_e32 v106, v98, v98
	v_max_f32_e32 v98, 0, v103
	v_max_f32_e32 v100, 0, v100
	s_waitcnt lgkmcnt(0)
	v_add_f32_e32 v103, v96, v97
	ds_bpermute_b32 v107, v175, v103
	v_mul_f32_e32 v97, v98, v98
	v_mul_f32_e32 v100, v100, v100
	v_cvt_pk_bf16_f32 v96, v100, v101
	v_max_f32_e32 v99, 0, v99
	s_waitcnt lgkmcnt(0)
; __device__ __forceinline__ float shx(float v, int lane, int mask) { return __int_as_float(__builtin_amdgcn_ds_bpermute((lane ^ mask) << 2, __float_as_int(v))); }
; __device__ __forceinline__ unsigned cvt_pk_bf16(float lo, float hi) { unsigned r; asm volatile("v_cvt_pk_bf16_f32 %0, %1, %2" : "=v"(r) : "v"(lo), "v"(hi)); return r; }
;     __device__ __forceinline__ void operator()(const f32x4 (&acc)[2][2][4][2], const Unit& u, int wr, int wc, int fr, int fq) const {
;     ...
; #pragma unroll
;         for (int ai = 0; ai < 2; ++ai)
; #pragma unroll
;             for (int m = 0; m < 4; ++m) {
;                 const int row = row0 + ai * 128 + m * 16;
;                 float ss = (sq[ai][m][0] + sq[ai][m][1]) + (sq[ai][m][2] + sq[ai][m][3]);
;                 ss += shx(ss, fq * 16 + fr, 16); ss += shx(ss, fq * 16 + fr, 32);
;                 const float rs = rsqrtf(ss * (1.0f / 1024.0f) + EPS);
; #pragma unroll
;                 for (int bj = 0; bj < 2; ++bj) {
;                     f32x4 v0 = acc[ai][bj][m][0] * rs, v1 = acc[ai][bj][m][1] * rs;
; #pragma unroll
;                     for (int j = 0; j < 4; ++j) { const float a = fmaxf(v0[j], 0.f), b = fmaxf(v1[j], 0.f); v0[j] = a * a; v1[j] = b * b; }
;                     u32x4 w; w.x = cvt_pk_bf16(v0[0], v0[1]); w.y = cvt_pk_bf16(v0[2], v0[3]); w.z = cvt_pk_bf16(v1[0], v1[1]); w.w = cvt_pk_bf16(v1[2], v1[3]);
;                     { const int col = col0 + bj * 128;
;                       *(u32x4*)(H + ((size_t)((row >> 8) * (DFF / 64) + (col >> 6)) * 256 + (row & 255)) * 64 + (col & 63)) = w; }
;                 }
	v_add_f32_e32 v98, v103, v107
	v_fmamk_f32 v98, v98, 0x3a800000, v181
	v_mul_f32_e32 v100, 0x4b800000, v98
	v_cmp_gt_f32_e32 vcc, s41, v98
	v_max_f32_e32 v102, 0, v102
	v_mul_f32_e32 v99, v99, v99
	v_cndmask_b32_e32 v98, v98, v100, vcc
	v_rsq_f32_e32 v100, v98
	v_mul_f32_e32 v102, v102, v102
	v_cvt_pk_bf16_f32 v97, v102, v97
	v_cvt_pk_bf16_f32 v98, v104, v105
	v_cvt_pk_bf16_f32 v99, v106, v99
	global_store_dwordx4 v[116:117], v[96:99], off offset:2048
	s_nop 1
	v_mul_f32_e32 v96, 0x45800000, v100
	v_cndmask_b32_e32 v96, v100, v96, vcc
	v_pk_mul_f32 v[90:91], v[90:91], v[96:97] op_sel_hi:[1,0]
	v_pk_mul_f32 v[88:89], v[88:89], v[96:97] op_sel_hi:[1,0]
	v_pk_mul_f32 v[94:95], v[94:95], v[96:97] op_sel_hi:[1,0]
	v_pk_mul_f32 v[92:93], v[92:93], v[96:97] op_sel_hi:[1,0]
	v_max_f32_e32 v88, 0, v88
	v_max_f32_e32 v89, 0, v89
	v_max_f32_e32 v90, 0, v90
	v_max_f32_e32 v92, 0, v92
	v_mul_f32_e32 v97, v88, v88
	v_max_f32_e32 v88, 0, v93
	v_mul_f32_e32 v93, v89, v89
	v_max_f32_e32 v89, 0, v94
	v_mul_f32_e32 v94, v90, v90
	v_max_f32_e32 v90, 0, v95
	v_mul_f32_e32 v92, v92, v92
	v_mul_f32_e32 v88, v88, v88
	v_mul_f32_e32 v89, v89, v89
	v_max_f32_e32 v91, 0, v91
	v_mul_f32_e32 v90, v90, v90
	v_mul_f32_e32 v91, v91, v91
	v_cvt_pk_bf16_f32 v88, v92, v88
	v_cvt_pk_bf16_f32 v89, v89, v90
	v_cvt_pk_bf16_f32 v90, v97, v93
	v_or_b32_e32 v92, 0x1000, v156
	v_mov_b32_e32 v93, v157
	v_cvt_pk_bf16_f32 v91, v94, v91
	v_lshl_add_u64 v[94:95], s[14:15], 0, v[92:93]
	v_pk_mul_f32 v[80:81], v[80:81], v[96:97] op_sel_hi:[1,0]
	v_lshl_add_u64 v[94:95], v[94:95], 0, v[168:169]
	v_pk_mul_f32 v[84:85], v[84:85], v[96:97] op_sel_hi:[1,0]
	v_max_f32_e32 v80, 0, v80
	global_store_dwordx4 v[94:95], v[88:91], off
	v_pk_mul_f32 v[86:87], v[86:87], v[96:97] op_sel_hi:[1,0]
	v_pk_mul_f32 v[82:83], v[82:83], v[96:97] op_sel_hi:[1,0]
	v_mul_f32_e32 v88, v80, v80
	v_max_f32_e32 v80, 0, v85
	v_max_f32_e32 v81, 0, v81
	v_mul_f32_e32 v85, v80, v80
	v_mul_f32_e32 v89, v81, v81
	v_max_f32_e32 v80, 0, v86
	v_max_f32_e32 v81, 0, v82
	v_mul_f32_e32 v82, v80, v80
	v_mul_f32_e32 v86, v81, v81
	v_mov_b32_e32 v80, v145
	v_mov_b32_e32 v81, v146
	v_mov_b32_e32 v145, v147
	v_pk_add_f32 v[80:81], v[80:81], v[144:145]
	v_max_f32_e32 v84, 0, v84
	v_add_f32_e32 v80, v80, v81
	ds_bpermute_b32 v81, v174, v80
	v_mul_f32_e32 v84, v84, v84
	v_max_f32_e32 v83, 0, v83
	v_max_f32_e32 v87, 0, v87
	v_mul_f32_e32 v83, v83, v83
	s_waitcnt lgkmcnt(0)
	v_add_f32_e32 v90, v80, v81
	ds_bpermute_b32 v91, v175, v90
	v_cvt_pk_bf16_f32 v80, v84, v85
	v_mul_f32_e32 v87, v87, v87
	v_cvt_pk_bf16_f32 v81, v82, v87
	v_cvt_pk_bf16_f32 v82, v88, v89
	s_waitcnt lgkmcnt(0)
	v_add_f32_e32 v84, v90, v91
	v_fmamk_f32 v84, v84, 0x3a800000, v181
	v_mul_f32_e32 v85, 0x4b800000, v84
	v_cmp_gt_f32_e32 vcc, s41, v84
	v_cvt_pk_bf16_f32 v83, v86, v83
	v_or_b32_e32 v156, 0x1800, v156
	s_nop 0
	v_cndmask_b32_e32 v84, v84, v85, vcc
	v_rsq_f32_e32 v86, v84
	v_lshl_add_u64 v[84:85], s[16:17], 0, v[92:93]
	v_lshl_add_u64 v[84:85], v[84:85], 0, v[168:169]
	global_store_dwordx4 v[84:85], v[80:83], off
	s_nop 1
	v_mul_f32_e32 v80, 0x45800000, v86
	v_cndmask_b32_e32 v80, v86, v80, vcc
	v_pk_mul_f32 v[74:75], v[74:75], v[80:81] op_sel_hi:[1,0]
	v_pk_mul_f32 v[72:73], v[72:73], v[80:81] op_sel_hi:[1,0]
	v_pk_mul_f32 v[78:79], v[78:79], v[80:81] op_sel_hi:[1,0]
	v_pk_mul_f32 v[76:77], v[76:77], v[80:81] op_sel_hi:[1,0]
	v_max_f32_e32 v72, 0, v72
	v_max_f32_e32 v73, 0, v73
	v_max_f32_e32 v74, 0, v74
	v_max_f32_e32 v76, 0, v76
	v_mul_f32_e32 v81, v72, v72
	v_max_f32_e32 v72, 0, v77
	v_mul_f32_e32 v77, v73, v73
	v_max_f32_e32 v73, 0, v78
	v_mul_f32_e32 v78, v74, v74
	v_max_f32_e32 v74, 0, v79
	v_mul_f32_e32 v76, v76, v76
	v_mul_f32_e32 v72, v72, v72
	v_mul_f32_e32 v73, v73, v73
	v_mul_f32_e32 v74, v74, v74
	v_max_f32_e32 v75, 0, v75
	v_cvt_pk_bf16_f32 v72, v76, v72
	v_cvt_pk_bf16_f32 v73, v73, v74
	v_cvt_pk_bf16_f32 v74, v81, v77
	v_lshl_add_u64 v[76:77], s[14:15], 0, v[156:157]
	v_pk_mul_f32 v[64:65], v[64:65], v[80:81] op_sel_hi:[1,0]
	v_mul_f32_e32 v75, v75, v75
	v_lshl_add_u64 v[76:77], v[76:77], 0, v[168:169]
	v_pk_mul_f32 v[68:69], v[68:69], v[80:81] op_sel_hi:[1,0]
	v_max_f32_e32 v64, 0, v64
	v_cvt_pk_bf16_f32 v75, v78, v75
	global_store_dwordx4 v[76:77], v[72:75], off
	v_pk_mul_f32 v[70:71], v[70:71], v[80:81] op_sel_hi:[1,0]
	v_pk_mul_f32 v[66:67], v[66:67], v[80:81] op_sel_hi:[1,0]
	v_mul_f32_e32 v72, v64, v64
	v_max_f32_e32 v64, 0, v69
	v_max_f32_e32 v65, 0, v65
	v_mul_f32_e32 v69, v64, v64
	v_mul_f32_e32 v73, v65, v65
	v_max_f32_e32 v64, 0, v70
	v_max_f32_e32 v65, 0, v66
	v_mul_f32_e32 v66, v64, v64
	v_mul_f32_e32 v70, v65, v65
	s_waitcnt vmcnt(10)
	v_mov_b32_e32 v64, v141
	v_mov_b32_e32 v65, v142
	v_mov_b32_e32 v141, v143
	v_pk_add_f32 v[64:65], v[64:65], v[140:141]
	v_max_f32_e32 v71, 0, v71
	v_add_f32_e32 v74, v64, v65
	ds_bpermute_b32 v75, v174, v74
	v_mul_f32_e32 v65, v71, v71
	v_max_f32_e32 v67, 0, v67
	v_max_f32_e32 v68, 0, v68
	v_mul_f32_e32 v67, v67, v67
	s_waitcnt lgkmcnt(0)
	v_add_f32_e32 v71, v74, v75
	ds_bpermute_b32 v74, v175, v71
	v_mul_f32_e32 v68, v68, v68
	v_cvt_pk_bf16_f32 v64, v68, v69
	v_cvt_pk_bf16_f32 v65, v66, v65
	v_cvt_pk_bf16_f32 v66, v72, v73
	v_cvt_pk_bf16_f32 v67, v70, v67
	s_waitcnt lgkmcnt(0)
; __device__ __forceinline__ float shx(float v, int lane, int mask) { return __int_as_float(__builtin_amdgcn_ds_bpermute((lane ^ mask) << 2, __float_as_int(v))); }
; __device__ __forceinline__ unsigned cvt_pk_bf16(float lo, float hi) { unsigned r; asm volatile("v_cvt_pk_bf16_f32 %0, %1, %2" : "=v"(r) : "v"(lo), "v"(hi)); return r; }
;     __device__ __forceinline__ void operator()(const f32x4 (&acc)[2][2][4][2], const Unit& u, int wr, int wc, int fr, int fq) const {
;     ...
; #pragma unroll
;         for (int ai = 0; ai < 2; ++ai)
; #pragma unroll
;             for (int m = 0; m < 4; ++m) {
;                 const int row = row0 + ai * 128 + m * 16;
;                 float ss = (sq[ai][m][0] + sq[ai][m][1]) + (sq[ai][m][2] + sq[ai][m][3]);
;                 ss += shx(ss, fq * 16 + fr, 16); ss += shx(ss, fq * 16 + fr, 32);
;                 const float rs = rsqrtf(ss * (1.0f / 1024.0f) + EPS);
; #pragma unroll
;                 for (int bj = 0; bj < 2; ++bj) {
;                     f32x4 v0 = acc[ai][bj][m][0] * rs, v1 = acc[ai][bj][m][1] * rs;
; #pragma unroll
;                     for (int j = 0; j < 4; ++j) { const float a = fmaxf(v0[j], 0.f), b = fmaxf(v1[j], 0.f); v0[j] = a * a; v1[j] = b * b; }
;                     u32x4 w; w.x = cvt_pk_bf16(v0[0], v0[1]); w.y = cvt_pk_bf16(v0[2], v0[3]); w.z = cvt_pk_bf16(v1[0], v1[1]); w.w = cvt_pk_bf16(v1[2], v1[3]);
;                     { const int col = col0 + bj * 128;
;                       *(u32x4*)(H + ((size_t)((row >> 8) * (DFF / 64) + (col >> 6)) * 256 + (row & 255)) * 64 + (col & 63)) = w; }
;                 }
	v_add_f32_e32 v70, v71, v74
	v_fmamk_f32 v70, v70, 0x3a800000, v181
	v_mul_f32_e32 v71, 0x4b800000, v70
	v_cmp_gt_f32_e32 vcc, s41, v70
	v_lshl_add_u64 v[68:69], s[16:17], 0, v[156:157]
	v_lshl_add_u64 v[68:69], v[68:69], 0, v[168:169]
	v_cndmask_b32_e32 v70, v70, v71, vcc
	v_rsq_f32_e32 v70, v70
	global_store_dwordx4 v[68:69], v[64:67], off
	s_mov_b32 s15, s6
	s_mov_b32 s14, s8
	v_ashrrev_i32_e32 v64, 2, v170
	v_and_b32_e32 v65, 0xffffffc0, v64
	v_mul_f32_e32 v64, 0x45800000, v70
	v_cndmask_b32_e32 v64, v70, v64, vcc
	v_pk_mul_f32 v[60:61], v[60:61], v[64:65] op_sel_hi:[1,0]
	v_pk_mul_f32 v[58:59], v[58:59], v[64:65] op_sel_hi:[1,0]
	v_pk_mul_f32 v[56:57], v[56:57], v[64:65] op_sel_hi:[1,0]
	v_pk_mul_f32 v[62:63], v[62:63], v[64:65] op_sel_hi:[1,0]
	v_max_f32_e32 v60, 0, v60
	v_max_f32_e32 v56, 0, v56
	v_max_f32_e32 v58, 0, v58
	v_mul_f32_e32 v60, v60, v60
	v_mul_f32_e32 v56, v56, v56
	v_max_f32_e32 v61, 0, v61
	v_max_f32_e32 v57, 0, v57
	v_max_f32_e32 v62, 0, v62
	v_mul_f32_e32 v66, v58, v58
	v_max_f32_e32 v58, 0, v63
	v_max_f32_e32 v59, 0, v59
	v_mul_f32_e32 v61, v61, v61
	v_mul_f32_e32 v57, v57, v57
	v_mul_f32_e32 v62, v62, v62
	v_mul_f32_e32 v63, v58, v58
	v_mul_f32_e32 v67, v59, v59
	v_cvt_pk_bf16_f32 v58, v60, v61
	v_cvt_pk_bf16_f32 v59, v62, v63
	v_cvt_pk_bf16_f32 v60, v56, v57
	v_add_u32_e32 v56, s7, v65
	v_ashrrev_i32_e32 v57, 31, v56
	v_lshlrev_b64 v[56:57], 15, v[56:57]
	v_lshlrev_b32_e32 v62, 7, v170
	v_lshl_add_u64 v[56:57], s[2:3], 0, v[56:57]
	v_and_b32_e32 v156, 0x6780, v62
	v_lshl_add_u64 v[62:63], v[56:57], 0, v[156:157]
	v_pk_mul_f32 v[48:49], v[48:49], v[64:65] op_sel_hi:[1,0]
	v_lshl_add_u64 v[62:63], v[62:63], 0, v[168:169]
	v_pk_mul_f32 v[52:53], v[52:53], v[64:65] op_sel_hi:[1,0]
	v_max_f32_e32 v48, 0, v48
	v_cvt_pk_bf16_f32 v61, v66, v67
	global_store_dwordx4 v[62:63], v[58:61], off
	v_pk_mul_f32 v[54:55], v[54:55], v[64:65] op_sel_hi:[1,0]
	v_pk_mul_f32 v[50:51], v[50:51], v[64:65] op_sel_hi:[1,0]
	v_mul_f32_e32 v58, v48, v48
	v_max_f32_e32 v48, 0, v53
	v_max_f32_e32 v49, 0, v49
	v_mul_f32_e32 v53, v48, v48
	v_mul_f32_e32 v59, v49, v49
	v_max_f32_e32 v48, 0, v54
	v_max_f32_e32 v49, 0, v50
	v_mul_f32_e32 v54, v48, v48
	v_mul_f32_e32 v60, v49, v49
	v_max_f32_e32 v48, 0, v55
	v_max_f32_e32 v49, 0, v51
	v_mul_f32_e32 v51, v48, v48
	v_mul_f32_e32 v55, v49, v49
	s_waitcnt vmcnt(11)
	v_mov_b32_e32 v48, v137
	v_mov_b32_e32 v49, v138
	v_mov_b32_e32 v137, v139
	v_pk_add_f32 v[48:49], v[48:49], v[136:137]
	v_max_f32_e32 v52, 0, v52
	v_add_f32_e32 v48, v48, v49
	ds_bpermute_b32 v49, v174, v48
	v_mul_f32_e32 v52, v52, v52
	v_cvt_pk_bf16_f32 v50, v52, v53
	v_cvt_pk_bf16_f32 v51, v54, v51
	v_cvt_pk_bf16_f32 v52, v58, v59
	s_waitcnt lgkmcnt(0)
	v_add_f32_e32 v54, v48, v49
	v_cvt_pk_bf16_f32 v53, v60, v55
	ds_bpermute_b32 v55, v175, v54
	v_add_u32_e32 v48, s9, v65
	v_ashrrev_i32_e32 v49, 31, v48
	v_lshlrev_b64 v[48:49], 15, v[48:49]
	v_lshl_add_u64 v[48:49], s[2:3], 0, v[48:49]
	s_waitcnt lgkmcnt(0)
	v_add_f32_e32 v54, v54, v55
	v_fmamk_f32 v54, v54, 0x3a800000, v181
	v_mul_f32_e32 v55, 0x4b800000, v54
	v_cmp_gt_f32_e32 vcc, s41, v54
	s_mov_b64 s[16:17], s[10:11]
	s_nop 0
	v_cndmask_b32_e32 v54, v54, v55, vcc
	v_rsq_f32_e32 v58, v54
	v_lshl_add_u64 v[54:55], v[48:49], 0, v[156:157]
	v_lshl_add_u64 v[54:55], v[54:55], 0, v[168:169]
	global_store_dwordx4 v[54:55], v[50:53], off
	s_nop 1
	v_mul_f32_e32 v50, 0x45800000, v58
	v_cndmask_b32_e32 v50, v58, v50, vcc
	v_pk_mul_f32 v[40:41], v[40:41], v[50:51] op_sel_hi:[1,0]
	v_pk_mul_f32 v[44:45], v[44:45], v[50:51] op_sel_hi:[1,0]
	v_pk_mul_f32 v[42:43], v[42:43], v[50:51] op_sel_hi:[1,0]
	v_max_f32_e32 v40, 0, v40
	v_pk_mul_f32 v[46:47], v[46:47], v[50:51] op_sel_hi:[1,0]
	v_mul_f32_e32 v51, v40, v40
	v_max_f32_e32 v40, 0, v45
	v_max_f32_e32 v41, 0, v41
	v_max_f32_e32 v42, 0, v42
	v_max_f32_e32 v44, 0, v44
	v_mul_f32_e32 v40, v40, v40
	v_mul_f32_e32 v45, v41, v41
	v_max_f32_e32 v41, 0, v46
	v_mul_f32_e32 v46, v42, v42
	v_max_f32_e32 v42, 0, v47
	v_max_f32_e32 v43, 0, v43
	v_pk_mul_f32 v[32:33], v[32:33], v[50:51] op_sel_hi:[1,0]
	v_mul_f32_e32 v44, v44, v44
	v_mul_f32_e32 v41, v41, v41
	v_mul_f32_e32 v42, v42, v42
	v_mul_f32_e32 v43, v43, v43
	v_cvt_pk_bf16_f32 v40, v44, v40
	v_pk_mul_f32 v[36:37], v[36:37], v[50:51] op_sel_hi:[1,0]
	v_max_f32_e32 v32, 0, v32
	v_cvt_pk_bf16_f32 v41, v41, v42
	v_cvt_pk_bf16_f32 v42, v51, v45
	v_cvt_pk_bf16_f32 v43, v46, v43
	global_store_dwordx4 v[62:63], v[40:43], off offset:2048
	v_max_f32_e32 v33, 0, v33
	v_pk_mul_f32 v[34:35], v[34:35], v[50:51] op_sel_hi:[1,0]
	v_mul_f32_e32 v40, v32, v32
	v_max_f32_e32 v32, 0, v37
	v_mul_f32_e32 v37, v32, v32
	v_mul_f32_e32 v41, v33, v33
	s_waitcnt vmcnt(12)
	v_mov_b32_e32 v32, v133
	v_mov_b32_e32 v33, v134
	v_mov_b32_e32 v133, v135
	v_pk_add_f32 v[32:33], v[32:33], v[132:133]
	v_pk_mul_f32 v[38:39], v[38:39], v[50:51] op_sel_hi:[1,0]
	v_add_f32_e32 v32, v32, v33
	ds_bpermute_b32 v33, v174, v32
	v_max_f32_e32 v34, 0, v34
	v_mul_f32_e32 v42, v34, v34
	v_max_f32_e32 v34, 0, v39
	v_max_f32_e32 v36, 0, v36
	s_waitcnt lgkmcnt(0)
	v_add_f32_e32 v39, v32, v33
	ds_bpermute_b32 v43, v175, v39
	v_mul_f32_e32 v33, v34, v34
	v_mul_f32_e32 v36, v36, v36
	v_cvt_pk_bf16_f32 v32, v36, v37
	v_max_f32_e32 v35, 0, v35
	s_waitcnt lgkmcnt(0)
; __device__ __forceinline__ float shx(float v, int lane, int mask) { return __int_as_float(__builtin_amdgcn_ds_bpermute((lane ^ mask) << 2, __float_as_int(v))); }
; __device__ __forceinline__ unsigned cvt_pk_bf16(float lo, float hi) { unsigned r; asm volatile("v_cvt_pk_bf16_f32 %0, %1, %2" : "=v"(r) : "v"(lo), "v"(hi)); return r; }
; #define PG8_WAIT_V(n) asm volatile("s_waitcnt vmcnt(" #n ")" ::: "memory")
; #define PG8_BAR __builtin_amdgcn_s_barrier()
; template <class Epi, class Sched>
; __device__ __forceinline__ void gemm_phase(const int wv, LAS unsigned char* lds, const Gemm g, const Sched& S, const Epi& E) {
;     ...
;     PG8_WAIT_V(0);
;     if (wr == 0) PG8_BAR;
;     PG8_BAR;
;     __device__ __forceinline__ void operator()(const f32x4 (&acc)[2][2][4][2], const Unit& u, int wr, int wc, int fr, int fq) const {
;     ...
; #pragma unroll
;         for (int ai = 0; ai < 2; ++ai)
; #pragma unroll
;             for (int m = 0; m < 4; ++m) {
;                 const int row = row0 + ai * 128 + m * 16;
;                 float ss = (sq[ai][m][0] + sq[ai][m][1]) + (sq[ai][m][2] + sq[ai][m][3]);
;                 ss += shx(ss, fq * 16 + fr, 16); ss += shx(ss, fq * 16 + fr, 32);
;                 const float rs = rsqrtf(ss * (1.0f / 1024.0f) + EPS);
; #pragma unroll
;                 for (int bj = 0; bj < 2; ++bj) {
;                     f32x4 v0 = acc[ai][bj][m][0] * rs, v1 = acc[ai][bj][m][1] * rs;
; #pragma unroll
;                     for (int j = 0; j < 4; ++j) { const float a = fmaxf(v0[j], 0.f), b = fmaxf(v1[j], 0.f); v0[j] = a * a; v1[j] = b * b; }
;                     u32x4 w; w.x = cvt_pk_bf16(v0[0], v0[1]); w.y = cvt_pk_bf16(v0[2], v0[3]); w.z = cvt_pk_bf16(v1[0], v1[1]); w.w = cvt_pk_bf16(v1[2], v1[3]);
;                     { const int col = col0 + bj * 128;
;                       *(u32x4*)(H + ((size_t)((row >> 8) * (DFF / 64) + (col >> 6)) * 256 + (row & 255)) * 64 + (col & 63)) = w; }
;                 }
	v_add_f32_e32 v34, v39, v43
	v_fmamk_f32 v34, v34, 0x3a800000, v181
	v_mul_f32_e32 v36, 0x4b800000, v34
	v_cmp_gt_f32_e32 vcc, s41, v34
	v_max_f32_e32 v38, 0, v38
	v_mul_f32_e32 v35, v35, v35
	v_cndmask_b32_e32 v34, v34, v36, vcc
	v_rsq_f32_e32 v36, v34
	v_mul_f32_e32 v38, v38, v38
	v_cvt_pk_bf16_f32 v33, v38, v33
	v_cvt_pk_bf16_f32 v34, v40, v41
	v_cvt_pk_bf16_f32 v35, v42, v35
	global_store_dwordx4 v[54:55], v[32:35], off offset:2048
	s_nop 1
	v_mul_f32_e32 v32, 0x45800000, v36
	v_cndmask_b32_e32 v32, v36, v32, vcc
	v_pk_mul_f32 v[26:27], v[26:27], v[32:33] op_sel_hi:[1,0]
	v_pk_mul_f32 v[24:25], v[24:25], v[32:33] op_sel_hi:[1,0]
	v_pk_mul_f32 v[30:31], v[30:31], v[32:33] op_sel_hi:[1,0]
	v_pk_mul_f32 v[28:29], v[28:29], v[32:33] op_sel_hi:[1,0]
	v_max_f32_e32 v24, 0, v24
	v_max_f32_e32 v25, 0, v25
	v_max_f32_e32 v26, 0, v26
	v_max_f32_e32 v28, 0, v28
	v_mul_f32_e32 v33, v24, v24
	v_max_f32_e32 v24, 0, v29
	v_mul_f32_e32 v29, v25, v25
	v_max_f32_e32 v25, 0, v30
	v_mul_f32_e32 v30, v26, v26
	v_max_f32_e32 v26, 0, v31
	v_mul_f32_e32 v28, v28, v28
	v_mul_f32_e32 v24, v24, v24
	v_mul_f32_e32 v25, v25, v25
	v_max_f32_e32 v27, 0, v27
	v_mul_f32_e32 v26, v26, v26
	v_mul_f32_e32 v27, v27, v27
	v_cvt_pk_bf16_f32 v24, v28, v24
	v_cvt_pk_bf16_f32 v25, v25, v26
	v_cvt_pk_bf16_f32 v26, v33, v29
	v_or_b32_e32 v28, 0x1000, v156
	v_mov_b32_e32 v29, v157
	v_cvt_pk_bf16_f32 v27, v30, v27
	v_lshl_add_u64 v[30:31], v[56:57], 0, v[28:29]
	v_pk_mul_f32 v[16:17], v[16:17], v[32:33] op_sel_hi:[1,0]
	v_lshl_add_u64 v[30:31], v[30:31], 0, v[168:169]
	v_pk_mul_f32 v[20:21], v[20:21], v[32:33] op_sel_hi:[1,0]
	v_max_f32_e32 v16, 0, v16
	global_store_dwordx4 v[30:31], v[24:27], off
	v_pk_mul_f32 v[22:23], v[22:23], v[32:33] op_sel_hi:[1,0]
	v_pk_mul_f32 v[18:19], v[18:19], v[32:33] op_sel_hi:[1,0]
	v_mul_f32_e32 v24, v16, v16
	v_max_f32_e32 v16, 0, v21
	v_max_f32_e32 v17, 0, v17
	v_mul_f32_e32 v21, v16, v16
	v_mul_f32_e32 v25, v17, v17
	v_max_f32_e32 v16, 0, v22
	v_max_f32_e32 v17, 0, v18
	v_mul_f32_e32 v18, v16, v16
	v_mul_f32_e32 v22, v17, v17
	s_waitcnt vmcnt(13)
	v_mov_b32_e32 v16, v129
	v_mov_b32_e32 v17, v130
	v_mov_b32_e32 v129, v131
	v_pk_add_f32 v[16:17], v[16:17], v[128:129]
	v_max_f32_e32 v20, 0, v20
	v_add_f32_e32 v16, v16, v17
	ds_bpermute_b32 v17, v174, v16
	v_mul_f32_e32 v20, v20, v20
	v_max_f32_e32 v19, 0, v19
	v_max_f32_e32 v23, 0, v23
	v_mul_f32_e32 v19, v19, v19
	s_waitcnt lgkmcnt(0)
	v_add_f32_e32 v26, v16, v17
	ds_bpermute_b32 v27, v175, v26
	v_cvt_pk_bf16_f32 v16, v20, v21
	v_mul_f32_e32 v23, v23, v23
	v_cvt_pk_bf16_f32 v17, v18, v23
	v_cvt_pk_bf16_f32 v18, v24, v25
	s_waitcnt lgkmcnt(0)
	v_add_f32_e32 v20, v26, v27
	v_fmamk_f32 v20, v20, 0x3a800000, v181
	v_mul_f32_e32 v21, 0x4b800000, v20
	v_cmp_gt_f32_e32 vcc, s41, v20
	v_cvt_pk_bf16_f32 v19, v22, v19
	v_or_b32_e32 v156, 0x1800, v156
	s_nop 0
	v_cndmask_b32_e32 v20, v20, v21, vcc
	v_rsq_f32_e32 v22, v20
	v_lshl_add_u64 v[20:21], v[48:49], 0, v[28:29]
	v_lshl_add_u64 v[20:21], v[20:21], 0, v[168:169]
	global_store_dwordx4 v[20:21], v[16:19], off
	s_nop 1
	v_mul_f32_e32 v16, 0x45800000, v22
	v_cndmask_b32_e32 v16, v22, v16, vcc
	v_pk_mul_f32 v[10:11], v[10:11], v[16:17] op_sel_hi:[1,0]
	v_pk_mul_f32 v[8:9], v[8:9], v[16:17] op_sel_hi:[1,0]
	v_pk_mul_f32 v[14:15], v[14:15], v[16:17] op_sel_hi:[1,0]
	v_pk_mul_f32 v[12:13], v[12:13], v[16:17] op_sel_hi:[1,0]
	v_max_f32_e32 v8, 0, v8
	v_max_f32_e32 v9, 0, v9
	v_max_f32_e32 v10, 0, v10
	v_max_f32_e32 v12, 0, v12
	v_mul_f32_e32 v17, v8, v8
	v_max_f32_e32 v8, 0, v13
	v_mul_f32_e32 v13, v9, v9
	v_max_f32_e32 v9, 0, v14
	v_mul_f32_e32 v14, v10, v10
	v_max_f32_e32 v10, 0, v15
	v_mul_f32_e32 v12, v12, v12
	v_mul_f32_e32 v8, v8, v8
	v_mul_f32_e32 v9, v9, v9
	v_mul_f32_e32 v10, v10, v10
	v_max_f32_e32 v11, 0, v11
	v_cvt_pk_bf16_f32 v8, v12, v8
	v_cvt_pk_bf16_f32 v9, v9, v10
	v_cvt_pk_bf16_f32 v10, v17, v13
	v_lshl_add_u64 v[12:13], v[56:57], 0, v[156:157]
	v_pk_mul_f32 v[2:3], v[2:3], v[16:17] op_sel_hi:[1,0]
	v_pk_mul_f32 v[0:1], v[0:1], v[16:17] op_sel_hi:[1,0]
	v_mul_f32_e32 v11, v11, v11
	v_lshl_add_u64 v[12:13], v[12:13], 0, v[168:169]
	v_pk_mul_f32 v[6:7], v[6:7], v[16:17] op_sel_hi:[1,0]
	v_pk_mul_f32 v[4:5], v[4:5], v[16:17] op_sel_hi:[1,0]
	v_max_f32_e32 v0, 0, v0
	v_max_f32_e32 v1, 0, v1
	v_max_f32_e32 v2, 0, v2
	v_cvt_pk_bf16_f32 v11, v14, v11
	global_store_dwordx4 v[12:13], v[8:11], off
	v_max_f32_e32 v4, 0, v4
	v_mul_f32_e32 v4, v4, v4
	v_mul_f32_e32 v8, v0, v0
	v_max_f32_e32 v0, 0, v5
	v_mul_f32_e32 v5, v1, v1
	v_max_f32_e32 v1, 0, v6
	v_mul_f32_e32 v6, v2, v2
	v_max_f32_e32 v2, 0, v7
	v_mul_f32_e32 v0, v0, v0
	v_mul_f32_e32 v1, v1, v1
	v_mul_f32_e32 v2, v2, v2
	v_max_f32_e32 v3, 0, v3
	v_cvt_pk_bf16_f32 v0, v4, v0
	v_cvt_pk_bf16_f32 v1, v1, v2
	v_cvt_pk_bf16_f32 v2, v8, v5
	v_lshl_add_u64 v[4:5], v[48:49], 0, v[156:157]
	v_mul_f32_e32 v3, v3, v3
	v_lshl_add_u64 v[4:5], v[4:5], 0, v[168:169]
	s_and_b64 vcc, exec, s[0:1]
	v_cvt_pk_bf16_f32 v3, v6, v3
	global_store_dwordx4 v[4:5], v[0:3], off
	s_cbranch_vccz .LBB0_718
	s_waitcnt vmcnt(0)
	s_cmpk_gt_u32 s22, 0xff
	s_cbranch_scc1 .LBB0_729
	s_barrier
